# combined plus: attention epilogue gate loads (16 per task) and half-tile w_out epilogue loads issued up front
# speedup vs baseline: 1.0092x; 1.0023x over previous
; DI void attn_task(const Params& P, int set, int b, int kvh, int qt, char* smem) {
;     ...
; #pragma unroll
;   for (int qi = 0; qi < 2; ++qi) {
;     const float ltot = l_run[qi] + __shfl_xor(l_run[qi], 32);
;     const float inv = 1.f / ltot;
;     const size_t row = row0 + 32 * qi;
; #pragma unroll
;     for (int db = 0; db < 2; ++db)
; #pragma unroll
;       for (int g = 0; g < 4; ++g) {
;         const size_t off = row * 512 + head * 64 + db * 32 + 8 * g + 4 * hh;
;         const half4 z = *(const half4*)(zs + off);
;         const f32x16& oo = o[qi][db];
;         *(half4*)(yc + row * LDY + head * 64 + db * 32 + 8 * g + 4 * hh) = cvt4(oo[4 * g] * inv * (float)z[0], oo[4 * g + 1] * inv * (float)z[1], oo[4 * g + 2] * inv * (float)z[2], oo[4 * g + 3] * inv * (float)z[3]);
;       }
;   }
.LBB0_69:
	v_readlane_b32 s2, v253, 31
	v_lshlrev_b32_e32 v128, 1, v174
	v_readlane_b32 s3, v253, 32
	v_lshlrev_b32_e32 v68, 3, v180
	v_mov_b32_e32 v69, v129
	v_lshl_add_u64 v[64:65], s[2:3], 0, v[128:129]
	v_readlane_b32 s2, v253, 33
	v_readlane_b32 s3, v253, 34
	v_lshl_add_u64 v[66:67], v[64:65], 0, v[68:69]
	v_mov_b32_e32 v216, v218
	v_lshl_add_u64 v[64:65], s[2:3], 0, v[128:129]
	v_lshl_add_u64 v[64:65], v[64:65], 0, v[68:69]
	ds_bpermute_b32 v68, v175, v169
	v_mad_u64_u32 v[64:65], s[2:3], v170, s4, v[64:65]
	v_mad_i32_i24 v65, v171, s4, v65
	s_waitcnt lgkmcnt(0)
	v_add_f32_e32 v68, v169, v68
	v_div_scale_f32 v69, s[2:3], v68, v68, 1.0
	v_rcp_f32_e32 v70, v69
	s_nop 0
	v_fma_f32 v71, -v69, v70, 1.0
	v_fmac_f32_e32 v70, v71, v70
	v_div_scale_f32 v71, vcc, 1.0, v68, 1.0
	v_mul_f32_e32 v72, v71, v70
	v_fma_f32 v73, -v69, v72, v71
	v_fmac_f32_e32 v72, v73, v70
	v_fma_f32 v69, -v69, v72, v71
	v_div_fmas_f32 v69, v69, v70, v72
	v_lshl_add_u64 v[70:71], v[66:67], 0, v[172:173]
	global_load_dwordx2 v[134:135], v[70:71], off
	global_load_dwordx2 v[136:137], v[70:71], off offset:16
	global_load_dwordx2 v[138:139], v[70:71], off offset:32
	global_load_dwordx2 v[140:141], v[70:71], off offset:48
	global_load_dwordx2 v[142:143], v[70:71], off offset:64
	global_load_dwordx2 v[144:145], v[70:71], off offset:80
	global_load_dwordx2 v[146:147], v[70:71], off offset:96
	global_load_dwordx2 v[148:149], v[70:71], off offset:112
	v_lshl_add_u64 v[132:133], v[66:67], 0, v[166:167]
	global_load_dwordx2 v[150:151], v[132:133], off
	global_load_dwordx2 v[152:153], v[132:133], off offset:16
	global_load_dwordx2 v[154:155], v[132:133], off offset:32
	global_load_dwordx2 v[156:157], v[132:133], off offset:48
	global_load_dwordx2 v[158:159], v[132:133], off offset:64
	global_load_dwordx2 v[160:161], v[132:133], off offset:80
	global_load_dwordx2 v[162:163], v[132:133], off offset:96
	global_load_dwordx2 v[164:165], v[132:133], off offset:112
	v_div_fixup_f32 v68, v69, v68, 1.0
	v_pk_mul_f32 v[48:49], v[48:49], v[68:69] op_sel_hi:[1,0]
	v_pk_mul_f32 v[50:51], v[50:51], v[68:69] op_sel_hi:[1,0]
	v_pk_mul_f32 v[32:33], v[32:33], v[68:69] op_sel_hi:[1,0]
	v_pk_mul_f32 v[34:35], v[34:35], v[68:69] op_sel_hi:[1,0]
	s_waitcnt vmcnt(0)
	v_mov_b32_e32 v72, v134
	v_mov_b32_e32 v73, v135
	v_cvt_f32_f16_e32 v74, v72
	v_cvt_f32_f16_sdwa v75, v72 dst_sel:DWORD dst_unused:UNUSED_PAD src0_sel:WORD_1
	v_cvt_f32_f16_e32 v72, v73
	v_cvt_f32_f16_sdwa v73, v73 dst_sel:DWORD dst_unused:UNUSED_PAD src0_sel:WORD_1
	v_pk_mul_f32 v[48:49], v[48:49], v[74:75]
	s_nop 0
	v_cvt_pk_f16_f32 v48, v48, v49
	v_pk_mul_f32 v[50:51], v[50:51], v[72:73]
	s_nop 0
	v_cvt_pk_f16_f32 v49, v50, v51
	global_store_dwordx2 v[64:65], v[48:49], off
	v_mov_b32_e32 v48, v136
	v_mov_b32_e32 v49, v137
	v_pk_mul_f32 v[50:51], v[52:53], v[68:69] op_sel_hi:[1,0]
	v_cvt_f32_f16_e32 v52, v48
	v_cvt_f32_f16_sdwa v53, v48 dst_sel:DWORD dst_unused:UNUSED_PAD src0_sel:WORD_1
	v_pk_mul_f32 v[50:51], v[50:51], v[52:53]
	v_cvt_f32_f16_e32 v52, v49
	v_cvt_f32_f16_sdwa v53, v49 dst_sel:DWORD dst_unused:UNUSED_PAD src0_sel:WORD_1
	v_cvt_pk_f16_f32 v48, v50, v51
	v_pk_mul_f32 v[50:51], v[54:55], v[68:69] op_sel_hi:[1,0]
	s_nop 0
	v_pk_mul_f32 v[50:51], v[50:51], v[52:53]
	s_nop 0
	v_cvt_pk_f16_f32 v49, v50, v51
	global_store_dwordx2 v[64:65], v[48:49], off offset:16
	v_mov_b32_e32 v48, v138
	v_mov_b32_e32 v49, v139
	v_pk_mul_f32 v[50:51], v[56:57], v[68:69] op_sel_hi:[1,0]
	v_cvt_f32_f16_e32 v52, v48
	v_cvt_f32_f16_sdwa v53, v48 dst_sel:DWORD dst_unused:UNUSED_PAD src0_sel:WORD_1
	v_pk_mul_f32 v[50:51], v[50:51], v[52:53]
	v_cvt_f32_f16_e32 v52, v49
	v_cvt_f32_f16_sdwa v53, v49 dst_sel:DWORD dst_unused:UNUSED_PAD src0_sel:WORD_1
	v_cvt_pk_f16_f32 v48, v50, v51
	v_pk_mul_f32 v[50:51], v[58:59], v[68:69] op_sel_hi:[1,0]
	s_nop 0
	v_pk_mul_f32 v[50:51], v[50:51], v[52:53]
	s_nop 0
	v_cvt_pk_f16_f32 v49, v50, v51
	global_store_dwordx2 v[64:65], v[48:49], off offset:32
	v_mov_b32_e32 v48, v140
	v_mov_b32_e32 v49, v141
	v_pk_mul_f32 v[50:51], v[60:61], v[68:69] op_sel_hi:[1,0]
	v_cvt_f32_f16_e32 v52, v48
	v_cvt_f32_f16_sdwa v53, v48 dst_sel:DWORD dst_unused:UNUSED_PAD src0_sel:WORD_1
	v_pk_mul_f32 v[50:51], v[50:51], v[52:53]
	v_cvt_f32_f16_e32 v52, v49
	v_cvt_f32_f16_sdwa v53, v49 dst_sel:DWORD dst_unused:UNUSED_PAD src0_sel:WORD_1
	v_cvt_pk_f16_f32 v48, v50, v51
	v_pk_mul_f32 v[50:51], v[62:63], v[68:69] op_sel_hi:[1,0]
	s_nop 0
	v_pk_mul_f32 v[50:51], v[50:51], v[52:53]
	s_nop 0
	v_cvt_pk_f16_f32 v49, v50, v51
	global_store_dwordx2 v[64:65], v[48:49], off offset:48
	v_mov_b32_e32 v48, v142
	v_mov_b32_e32 v49, v143
	v_cvt_f32_f16_e32 v50, v48
	v_cvt_f32_f16_sdwa v51, v48 dst_sel:DWORD dst_unused:UNUSED_PAD src0_sel:WORD_1
	v_cvt_f32_f16_e32 v48, v49
	v_cvt_f32_f16_sdwa v49, v49 dst_sel:DWORD dst_unused:UNUSED_PAD src0_sel:WORD_1
	v_pk_mul_f32 v[32:33], v[32:33], v[50:51]
	s_nop 0
	v_cvt_pk_f16_f32 v32, v32, v33
	v_pk_mul_f32 v[34:35], v[34:35], v[48:49]
	s_nop 0
	v_cvt_pk_f16_f32 v33, v34, v35
	global_store_dwordx2 v[64:65], v[32:33], off offset:64
	v_mov_b32_e32 v32, v144
	v_mov_b32_e32 v33, v145
	v_pk_mul_f32 v[34:35], v[36:37], v[68:69] op_sel_hi:[1,0]
	v_cvt_f32_f16_e32 v36, v32
	v_cvt_f32_f16_sdwa v37, v32 dst_sel:DWORD dst_unused:UNUSED_PAD src0_sel:WORD_1
	v_pk_mul_f32 v[34:35], v[34:35], v[36:37]
	v_cvt_f32_f16_e32 v36, v33
	v_cvt_f32_f16_sdwa v37, v33 dst_sel:DWORD dst_unused:UNUSED_PAD src0_sel:WORD_1
	v_cvt_pk_f16_f32 v32, v34, v35
	v_pk_mul_f32 v[34:35], v[38:39], v[68:69] op_sel_hi:[1,0]
	s_nop 0
	v_pk_mul_f32 v[34:35], v[34:35], v[36:37]
	s_nop 0
	v_cvt_pk_f16_f32 v33, v34, v35
	global_store_dwordx2 v[64:65], v[32:33], off offset:80
	v_mov_b32_e32 v32, v146
	v_mov_b32_e32 v33, v147
	v_pk_mul_f32 v[34:35], v[40:41], v[68:69] op_sel_hi:[1,0]
	v_cvt_f32_f16_e32 v36, v32
	v_cvt_f32_f16_sdwa v37, v32 dst_sel:DWORD dst_unused:UNUSED_PAD src0_sel:WORD_1
	v_pk_mul_f32 v[34:35], v[34:35], v[36:37]
	v_cvt_f32_f16_e32 v36, v33
	v_cvt_f32_f16_sdwa v37, v33 dst_sel:DWORD dst_unused:UNUSED_PAD src0_sel:WORD_1
	v_cvt_pk_f16_f32 v32, v34, v35
	v_pk_mul_f32 v[34:35], v[42:43], v[68:69] op_sel_hi:[1,0]
	s_nop 0
	v_pk_mul_f32 v[34:35], v[34:35], v[36:37]
	s_nop 0
	v_cvt_pk_f16_f32 v33, v34, v35
	global_store_dwordx2 v[64:65], v[32:33], off offset:96
	v_mov_b32_e32 v32, v148
	v_mov_b32_e32 v33, v149
	v_pk_mul_f32 v[34:35], v[44:45], v[68:69] op_sel_hi:[1,0]
	v_cvt_f32_f16_e32 v36, v32
	v_cvt_f32_f16_sdwa v37, v32 dst_sel:DWORD dst_unused:UNUSED_PAD src0_sel:WORD_1
	v_pk_mul_f32 v[34:35], v[34:35], v[36:37]
	v_cvt_f32_f16_e32 v36, v33
	v_cvt_f32_f16_sdwa v37, v33 dst_sel:DWORD dst_unused:UNUSED_PAD src0_sel:WORD_1
	v_cvt_pk_f16_f32 v32, v34, v35
	v_pk_mul_f32 v[34:35], v[46:47], v[68:69] op_sel_hi:[1,0]
	s_nop 0
	v_pk_mul_f32 v[34:35], v[34:35], v[36:37]
	s_nop 0
	v_cvt_pk_f16_f32 v33, v34, v35
	global_store_dwordx2 v[64:65], v[32:33], off offset:112
	ds_bpermute_b32 v32, v175, v168
	s_waitcnt lgkmcnt(0)
; DI void attn_task(const Params& P, int set, int b, int kvh, int qt, char* smem) {
;     ...
; #pragma unroll
;   for (int qi = 0; qi < 2; ++qi) {
;     const float ltot = l_run[qi] + __shfl_xor(l_run[qi], 32);
;     const float inv = 1.f / ltot;
;     const size_t row = row0 + 32 * qi;
; #pragma unroll
;     for (int db = 0; db < 2; ++db)
; #pragma unroll
;       for (int g = 0; g < 4; ++g) {
;         const size_t off = row * 512 + head * 64 + db * 32 + 8 * g + 4 * hh;
;         const half4 z = *(const half4*)(zs + off);
;         const f32x16& oo = o[qi][db];
;         *(half4*)(yc + row * LDY + head * 64 + db * 32 + 8 * g + 4 * hh) = cvt4(oo[4 * g] * inv * (float)z[0], oo[4 * g + 1] * inv * (float)z[1], oo[4 * g + 2] * inv * (float)z[2], oo[4 * g + 3] * inv * (float)z[3]);
;       }
;   }
	v_add_f32_e32 v32, v168, v32
	v_div_scale_f32 v33, s[2:3], v32, v32, 1.0
	v_rcp_f32_e32 v34, v33
	s_mov_b64 s[2:3], 0x9000
	v_fma_f32 v35, -v33, v34, 1.0
	v_fmac_f32_e32 v34, v35, v34
	v_div_scale_f32 v35, vcc, 1.0, v32, 1.0
	v_mul_f32_e32 v36, v35, v34
	v_fma_f32 v37, -v33, v36, v35
	v_fmac_f32_e32 v36, v37, v34
	v_fma_f32 v33, -v33, v36, v35
	v_div_fmas_f32 v33, v33, v34, v36
	v_lshl_add_u64 v[34:35], v[66:67], 0, v[166:167]
	v_mov_b32_e32 v38, v150
	v_mov_b32_e32 v39, v151
	v_div_fixup_f32 v32, v33, v32, 1.0
	v_pk_mul_f32 v[16:17], v[16:17], v[32:33] op_sel_hi:[1,0]
	v_pk_mul_f32 v[18:19], v[18:19], v[32:33] op_sel_hi:[1,0]
	v_lshl_add_u64 v[36:37], v[64:65], 0, s[2:3]
	v_cvt_f32_f16_e32 v40, v38
	v_cvt_f32_f16_sdwa v41, v38 dst_sel:DWORD dst_unused:UNUSED_PAD src0_sel:WORD_1
	v_cvt_f32_f16_e32 v38, v39
	v_cvt_f32_f16_sdwa v39, v39 dst_sel:DWORD dst_unused:UNUSED_PAD src0_sel:WORD_1
	v_pk_mul_f32 v[16:17], v[16:17], v[40:41]
	s_nop 0
	v_cvt_pk_f16_f32 v16, v16, v17
	v_pk_mul_f32 v[18:19], v[18:19], v[38:39]
	s_nop 0
	v_cvt_pk_f16_f32 v17, v18, v19
	v_add_co_u32_e32 v18, vcc, 0x9000, v64
	s_nop 1
	v_addc_co_u32_e32 v19, vcc, 0, v65, vcc
	global_store_dwordx2 v[18:19], v[16:17], off
.LBB0_70:
	v_mov_b32_e32 v16, v152
	v_mov_b32_e32 v17, v153
	v_mov_b32_e32 v33, v32
	v_pk_mul_f32 v[18:19], v[20:21], v[32:33]
	v_pk_mul_f32 v[0:1], v[32:33], v[0:1]
	v_pk_mul_f32 v[2:3], v[32:33], v[2:3]
	v_cvt_f32_f16_sdwa v21, v16 dst_sel:DWORD dst_unused:UNUSED_PAD src0_sel:WORD_1
	v_cvt_f32_f16_e32 v20, v16
	v_pk_mul_f32 v[18:19], v[18:19], v[20:21]
	v_cvt_f32_f16_sdwa v21, v17 dst_sel:DWORD dst_unused:UNUSED_PAD src0_sel:WORD_1
	v_cvt_f32_f16_e32 v20, v17
	v_cvt_pk_f16_f32 v16, v18, v19
	v_pk_mul_f32 v[18:19], v[22:23], v[32:33]
	s_nop 0
	v_pk_mul_f32 v[18:19], v[18:19], v[20:21]
	s_nop 0
	v_cvt_pk_f16_f32 v17, v18, v19
	global_store_dwordx2 v[36:37], v[16:17], off offset:16
	v_mov_b32_e32 v16, v154
	v_mov_b32_e32 v17, v155
	v_pk_mul_f32 v[18:19], v[24:25], v[32:33]
	v_cvt_f32_f16_sdwa v21, v16 dst_sel:DWORD dst_unused:UNUSED_PAD src0_sel:WORD_1
	v_cvt_f32_f16_e32 v20, v16
	v_pk_mul_f32 v[18:19], v[18:19], v[20:21]
	v_cvt_f32_f16_sdwa v21, v17 dst_sel:DWORD dst_unused:UNUSED_PAD src0_sel:WORD_1
	v_cvt_f32_f16_e32 v20, v17
	v_cvt_pk_f16_f32 v16, v18, v19
	v_pk_mul_f32 v[18:19], v[26:27], v[32:33]
	s_nop 0
	v_pk_mul_f32 v[18:19], v[18:19], v[20:21]
	s_nop 0
	v_cvt_pk_f16_f32 v17, v18, v19
	global_store_dwordx2 v[36:37], v[16:17], off offset:32
	v_mov_b32_e32 v16, v156
	v_mov_b32_e32 v17, v157
	v_pk_mul_f32 v[18:19], v[28:29], v[32:33]
	v_cvt_f32_f16_sdwa v21, v16 dst_sel:DWORD dst_unused:UNUSED_PAD src0_sel:WORD_1
	v_cvt_f32_f16_e32 v20, v16
	v_pk_mul_f32 v[18:19], v[18:19], v[20:21]
	v_cvt_f32_f16_sdwa v21, v17 dst_sel:DWORD dst_unused:UNUSED_PAD src0_sel:WORD_1
	v_cvt_f32_f16_e32 v20, v17
	v_cvt_pk_f16_f32 v16, v18, v19
	v_pk_mul_f32 v[18:19], v[30:31], v[32:33]
	s_nop 0
	v_pk_mul_f32 v[18:19], v[18:19], v[20:21]
	s_nop 0
	v_cvt_pk_f16_f32 v17, v18, v19
	global_store_dwordx2 v[36:37], v[16:17], off offset:48
	v_mov_b32_e32 v16, v158
	v_mov_b32_e32 v17, v159
	v_cvt_f32_f16_sdwa v19, v16 dst_sel:DWORD dst_unused:UNUSED_PAD src0_sel:WORD_1
	v_cvt_f32_f16_e32 v18, v16
	v_pk_mul_f32 v[0:1], v[0:1], v[18:19]
	v_cvt_f32_f16_sdwa v19, v17 dst_sel:DWORD dst_unused:UNUSED_PAD src0_sel:WORD_1
	v_cvt_f32_f16_e32 v18, v17
	v_cvt_pk_f16_f32 v0, v0, v1
	v_pk_mul_f32 v[2:3], v[2:3], v[18:19]
	s_nop 0
	v_cvt_pk_f16_f32 v1, v2, v3
	global_store_dwordx2 v[36:37], v[0:1], off offset:64
	v_mov_b32_e32 v0, v160
	v_mov_b32_e32 v1, v161
	v_pk_mul_f32 v[2:3], v[32:33], v[4:5]
	v_cvt_f32_f16_sdwa v5, v0 dst_sel:DWORD dst_unused:UNUSED_PAD src0_sel:WORD_1
	v_cvt_f32_f16_e32 v4, v0
	v_pk_mul_f32 v[2:3], v[2:3], v[4:5]
	v_cvt_f32_f16_sdwa v5, v1 dst_sel:DWORD dst_unused:UNUSED_PAD src0_sel:WORD_1
	v_cvt_f32_f16_e32 v4, v1
	v_cvt_pk_f16_f32 v0, v2, v3
	v_pk_mul_f32 v[2:3], v[32:33], v[6:7]
	s_nop 0
	v_pk_mul_f32 v[2:3], v[2:3], v[4:5]
	s_nop 0
	v_cvt_pk_f16_f32 v1, v2, v3
	global_store_dwordx2 v[36:37], v[0:1], off offset:80
	v_mov_b32_e32 v0, v162
	v_mov_b32_e32 v1, v163
	v_pk_mul_f32 v[2:3], v[32:33], v[8:9]
	v_cvt_f32_f16_sdwa v5, v0 dst_sel:DWORD dst_unused:UNUSED_PAD src0_sel:WORD_1
	v_cvt_f32_f16_e32 v4, v0
	v_pk_mul_f32 v[2:3], v[2:3], v[4:5]
	v_cvt_f32_f16_sdwa v5, v1 dst_sel:DWORD dst_unused:UNUSED_PAD src0_sel:WORD_1
	v_cvt_f32_f16_e32 v4, v1
	v_cvt_pk_f16_f32 v0, v2, v3
	v_pk_mul_f32 v[2:3], v[32:33], v[10:11]
	s_nop 0
	v_pk_mul_f32 v[2:3], v[2:3], v[4:5]
	s_nop 0
	v_cvt_pk_f16_f32 v1, v2, v3
	global_store_dwordx2 v[36:37], v[0:1], off offset:96
	v_mov_b32_e32 v0, v164
	v_mov_b32_e32 v1, v165
	v_pk_mul_f32 v[2:3], v[32:33], v[12:13]
	v_cvt_f32_f16_sdwa v5, v0 dst_sel:DWORD dst_unused:UNUSED_PAD src0_sel:WORD_1
	v_cvt_f32_f16_e32 v4, v0
	v_pk_mul_f32 v[2:3], v[2:3], v[4:5]
	v_cvt_f32_f16_sdwa v5, v1 dst_sel:DWORD dst_unused:UNUSED_PAD src0_sel:WORD_1
	v_cvt_f32_f16_e32 v4, v1
	v_cvt_pk_f16_f32 v0, v2, v3
	v_pk_mul_f32 v[2:3], v[32:33], v[14:15]
	s_nop 0
	v_pk_mul_f32 v[2:3], v[2:3], v[4:5]
	s_nop 0
	v_cvt_pk_f16_f32 v1, v2, v3
	global_store_dwordx2 v[36:37], v[0:1], off offset:112
	s_load_dword s2, s[36:37], 0x0
	s_waitcnt lgkmcnt(0)
	s_add_i32 s42, s2, s42

; DI void attn_task(const Params& P, int set, int b, int kvh, int qt, char* smem) {
;     ...
; #pragma unroll
;   for (int qi = 0; qi < 2; ++qi) {
;     const float ltot = l_run[qi] + __shfl_xor(l_run[qi], 32);
;     const float inv = 1.f / ltot;
;     const size_t row = row0 + 32 * qi;
; #pragma unroll
;     for (int db = 0; db < 2; ++db)
; #pragma unroll
;       for (int g = 0; g < 4; ++g) {
;         const size_t off = row * 512 + head * 64 + db * 32 + 8 * g + 4 * hh;
;         const half4 z = *(const half4*)(zs + off);
;         const f32x16& oo = o[qi][db];
;         *(half4*)(yc + row * LDY + head * 64 + db * 32 + 8 * g + 4 * hh) = cvt4(oo[4 * g] * inv * (float)z[0], oo[4 * g + 1] * inv * (float)z[1], oo[4 * g + 2] * inv * (float)z[2], oo[4 * g + 3] * inv * (float)z[3]);
;       }
;   }
.LBB0_81:
	v_readlane_b32 s2, v253, 31
	v_lshlrev_b32_e32 v128, 1, v174
	v_readlane_b32 s3, v253, 32
	v_lshlrev_b32_e32 v68, 3, v180
	v_mov_b32_e32 v69, v129
	v_lshl_add_u64 v[64:65], s[2:3], 0, v[128:129]
	v_readlane_b32 s2, v253, 33
	v_readlane_b32 s3, v253, 34
	v_lshl_add_u64 v[66:67], v[64:65], 0, v[68:69]
	v_mov_b32_e32 v216, v218
	v_lshl_add_u64 v[64:65], s[2:3], 0, v[128:129]
	v_lshl_add_u64 v[64:65], v[64:65], 0, v[68:69]
	ds_bpermute_b32 v68, v175, v169
	v_mad_u64_u32 v[64:65], s[2:3], v170, s4, v[64:65]
	v_mad_i32_i24 v65, v171, s4, v65
	s_waitcnt lgkmcnt(0)
	v_add_f32_e32 v68, v169, v68
	v_div_scale_f32 v69, s[2:3], v68, v68, 1.0
	v_rcp_f32_e32 v70, v69
	s_nop 0
	v_fma_f32 v71, -v69, v70, 1.0
	v_fmac_f32_e32 v70, v71, v70
	v_div_scale_f32 v71, vcc, 1.0, v68, 1.0
	v_mul_f32_e32 v72, v71, v70
	v_fma_f32 v73, -v69, v72, v71
	v_fmac_f32_e32 v72, v73, v70
	v_fma_f32 v69, -v69, v72, v71
	v_div_fmas_f32 v69, v69, v70, v72
	v_lshl_add_u64 v[70:71], v[66:67], 0, v[172:173]
	global_load_dwordx2 v[72:73], v[70:71], off
	v_div_fixup_f32 v68, v69, v68, 1.0
	v_pk_mul_f32 v[48:49], v[48:49], v[68:69] op_sel_hi:[1,0]
	v_pk_mul_f32 v[50:51], v[50:51], v[68:69] op_sel_hi:[1,0]
	v_pk_mul_f32 v[32:33], v[32:33], v[68:69] op_sel_hi:[1,0]
	v_pk_mul_f32 v[34:35], v[34:35], v[68:69] op_sel_hi:[1,0]
	s_waitcnt vmcnt(0)
	v_cvt_f32_f16_e32 v74, v72
	v_cvt_f32_f16_sdwa v75, v72 dst_sel:DWORD dst_unused:UNUSED_PAD src0_sel:WORD_1
	v_cvt_f32_f16_e32 v72, v73
	v_cvt_f32_f16_sdwa v73, v73 dst_sel:DWORD dst_unused:UNUSED_PAD src0_sel:WORD_1
	v_pk_mul_f32 v[48:49], v[48:49], v[74:75]
	s_nop 0
	v_cvt_pk_f16_f32 v48, v48, v49
	v_pk_mul_f32 v[50:51], v[50:51], v[72:73]
	s_nop 0
	v_cvt_pk_f16_f32 v49, v50, v51
	global_store_dwordx2 v[64:65], v[48:49], off
	global_load_dwordx2 v[48:49], v[70:71], off offset:16
	v_pk_mul_f32 v[50:51], v[52:53], v[68:69] op_sel_hi:[1,0]
	s_waitcnt vmcnt(0)
	v_cvt_f32_f16_e32 v52, v48
	v_cvt_f32_f16_sdwa v53, v48 dst_sel:DWORD dst_unused:UNUSED_PAD src0_sel:WORD_1
	v_pk_mul_f32 v[50:51], v[50:51], v[52:53]
	v_cvt_f32_f16_e32 v52, v49
	v_cvt_f32_f16_sdwa v53, v49 dst_sel:DWORD dst_unused:UNUSED_PAD src0_sel:WORD_1
	v_cvt_pk_f16_f32 v48, v50, v51
	v_pk_mul_f32 v[50:51], v[54:55], v[68:69] op_sel_hi:[1,0]
	s_nop 0
	v_pk_mul_f32 v[50:51], v[50:51], v[52:53]
	s_nop 0
	v_cvt_pk_f16_f32 v49, v50, v51
	global_store_dwordx2 v[64:65], v[48:49], off offset:16
	global_load_dwordx2 v[48:49], v[70:71], off offset:32
	v_pk_mul_f32 v[50:51], v[56:57], v[68:69] op_sel_hi:[1,0]
	s_waitcnt vmcnt(0)
	v_cvt_f32_f16_e32 v52, v48
	v_cvt_f32_f16_sdwa v53, v48 dst_sel:DWORD dst_unused:UNUSED_PAD src0_sel:WORD_1
	v_pk_mul_f32 v[50:51], v[50:51], v[52:53]
	v_cvt_f32_f16_e32 v52, v49
	v_cvt_f32_f16_sdwa v53, v49 dst_sel:DWORD dst_unused:UNUSED_PAD src0_sel:WORD_1
	v_cvt_pk_f16_f32 v48, v50, v51
	v_pk_mul_f32 v[50:51], v[58:59], v[68:69] op_sel_hi:[1,0]
	s_nop 0
	v_pk_mul_f32 v[50:51], v[50:51], v[52:53]
	s_nop 0
	v_cvt_pk_f16_f32 v49, v50, v51
	global_store_dwordx2 v[64:65], v[48:49], off offset:32
	global_load_dwordx2 v[48:49], v[70:71], off offset:48
	v_pk_mul_f32 v[50:51], v[60:61], v[68:69] op_sel_hi:[1,0]
	s_waitcnt vmcnt(0)
	v_cvt_f32_f16_e32 v52, v48
	v_cvt_f32_f16_sdwa v53, v48 dst_sel:DWORD dst_unused:UNUSED_PAD src0_sel:WORD_1
	v_pk_mul_f32 v[50:51], v[50:51], v[52:53]
	v_cvt_f32_f16_e32 v52, v49
	v_cvt_f32_f16_sdwa v53, v49 dst_sel:DWORD dst_unused:UNUSED_PAD src0_sel:WORD_1
	v_cvt_pk_f16_f32 v48, v50, v51
	v_pk_mul_f32 v[50:51], v[62:63], v[68:69] op_sel_hi:[1,0]
	s_nop 0
	v_pk_mul_f32 v[50:51], v[50:51], v[52:53]
	s_nop 0
	v_cvt_pk_f16_f32 v49, v50, v51
	global_store_dwordx2 v[64:65], v[48:49], off offset:48
	global_load_dwordx2 v[48:49], v[70:71], off offset:64
	s_waitcnt vmcnt(0)
; DI void attn_task(const Params& P, int set, int b, int kvh, int qt, char* smem) {
;     ...
; #pragma unroll
;   for (int qi = 0; qi < 2; ++qi) {
;     const float ltot = l_run[qi] + __shfl_xor(l_run[qi], 32);
;     const float inv = 1.f / ltot;
;     const size_t row = row0 + 32 * qi;
; #pragma unroll
;     for (int db = 0; db < 2; ++db)
; #pragma unroll
;       for (int g = 0; g < 4; ++g) {
;         const size_t off = row * 512 + head * 64 + db * 32 + 8 * g + 4 * hh;
;         const half4 z = *(const half4*)(zs + off);
;         const f32x16& oo = o[qi][db];
;         *(half4*)(yc + row * LDY + head * 64 + db * 32 + 8 * g + 4 * hh) = cvt4(oo[4 * g] * inv * (float)z[0], oo[4 * g + 1] * inv * (float)z[1], oo[4 * g + 2] * inv * (float)z[2], oo[4 * g + 3] * inv * (float)z[3]);
;       }
;   }
	v_cvt_f32_f16_e32 v50, v48
	v_cvt_f32_f16_sdwa v51, v48 dst_sel:DWORD dst_unused:UNUSED_PAD src0_sel:WORD_1
	v_cvt_f32_f16_e32 v48, v49
	v_cvt_f32_f16_sdwa v49, v49 dst_sel:DWORD dst_unused:UNUSED_PAD src0_sel:WORD_1
	v_pk_mul_f32 v[32:33], v[32:33], v[50:51]
	s_nop 0
	v_cvt_pk_f16_f32 v32, v32, v33
	v_pk_mul_f32 v[34:35], v[34:35], v[48:49]
	s_nop 0
	v_cvt_pk_f16_f32 v33, v34, v35
	global_store_dwordx2 v[64:65], v[32:33], off offset:64
	global_load_dwordx2 v[32:33], v[70:71], off offset:80
	v_pk_mul_f32 v[34:35], v[36:37], v[68:69] op_sel_hi:[1,0]
	s_waitcnt vmcnt(0)
	v_cvt_f32_f16_e32 v36, v32
	v_cvt_f32_f16_sdwa v37, v32 dst_sel:DWORD dst_unused:UNUSED_PAD src0_sel:WORD_1
	v_pk_mul_f32 v[34:35], v[34:35], v[36:37]
	v_cvt_f32_f16_e32 v36, v33
	v_cvt_f32_f16_sdwa v37, v33 dst_sel:DWORD dst_unused:UNUSED_PAD src0_sel:WORD_1
	v_cvt_pk_f16_f32 v32, v34, v35
	v_pk_mul_f32 v[34:35], v[38:39], v[68:69] op_sel_hi:[1,0]
	s_nop 0
	v_pk_mul_f32 v[34:35], v[34:35], v[36:37]
	s_nop 0
	v_cvt_pk_f16_f32 v33, v34, v35
	global_store_dwordx2 v[64:65], v[32:33], off offset:80
	global_load_dwordx2 v[32:33], v[70:71], off offset:96
	v_pk_mul_f32 v[34:35], v[40:41], v[68:69] op_sel_hi:[1,0]
	s_waitcnt vmcnt(0)
	v_cvt_f32_f16_e32 v36, v32
	v_cvt_f32_f16_sdwa v37, v32 dst_sel:DWORD dst_unused:UNUSED_PAD src0_sel:WORD_1
	v_pk_mul_f32 v[34:35], v[34:35], v[36:37]
	v_cvt_f32_f16_e32 v36, v33
	v_cvt_f32_f16_sdwa v37, v33 dst_sel:DWORD dst_unused:UNUSED_PAD src0_sel:WORD_1
	v_cvt_pk_f16_f32 v32, v34, v35
	v_pk_mul_f32 v[34:35], v[42:43], v[68:69] op_sel_hi:[1,0]
	s_nop 0
	v_pk_mul_f32 v[34:35], v[34:35], v[36:37]
	s_nop 0
	v_cvt_pk_f16_f32 v33, v34, v35
	global_store_dwordx2 v[64:65], v[32:33], off offset:96
	global_load_dwordx2 v[32:33], v[70:71], off offset:112
	v_pk_mul_f32 v[34:35], v[44:45], v[68:69] op_sel_hi:[1,0]
	s_waitcnt vmcnt(0)
	v_cvt_f32_f16_e32 v36, v32
	v_cvt_f32_f16_sdwa v37, v32 dst_sel:DWORD dst_unused:UNUSED_PAD src0_sel:WORD_1
	v_pk_mul_f32 v[34:35], v[34:35], v[36:37]
	v_cvt_f32_f16_e32 v36, v33
	v_cvt_f32_f16_sdwa v37, v33 dst_sel:DWORD dst_unused:UNUSED_PAD src0_sel:WORD_1
	v_cvt_pk_f16_f32 v32, v34, v35
	v_pk_mul_f32 v[34:35], v[46:47], v[68:69] op_sel_hi:[1,0]
	s_nop 0
	v_pk_mul_f32 v[34:35], v[34:35], v[36:37]
	s_nop 0
	v_cvt_pk_f16_f32 v33, v34, v35
	global_store_dwordx2 v[64:65], v[32:33], off offset:112
	ds_bpermute_b32 v32, v175, v168
	s_waitcnt lgkmcnt(0)
	v_add_f32_e32 v32, v168, v32
	v_div_scale_f32 v33, s[2:3], v32, v32, 1.0
	v_rcp_f32_e32 v34, v33
	s_mov_b64 s[2:3], 0x9000
	v_fma_f32 v35, -v33, v34, 1.0
	v_fmac_f32_e32 v34, v35, v34
	v_div_scale_f32 v35, vcc, 1.0, v32, 1.0
	v_mul_f32_e32 v36, v35, v34
	v_fma_f32 v37, -v33, v36, v35
	v_fmac_f32_e32 v36, v37, v34
	v_fma_f32 v33, -v33, v36, v35
	v_div_fmas_f32 v33, v33, v34, v36
	v_lshl_add_u64 v[34:35], v[66:67], 0, v[166:167]
	global_load_dwordx2 v[38:39], v[34:35], off
	global_load_dwordx2 v[152:153], v[34:35], off offset:16
	global_load_dwordx2 v[154:155], v[34:35], off offset:32
	global_load_dwordx2 v[156:157], v[34:35], off offset:48
	global_load_dwordx2 v[158:159], v[34:35], off offset:64
	global_load_dwordx2 v[160:161], v[34:35], off offset:80
	global_load_dwordx2 v[162:163], v[34:35], off offset:96
	global_load_dwordx2 v[164:165], v[34:35], off offset:112
	v_div_fixup_f32 v32, v33, v32, 1.0
	v_pk_mul_f32 v[16:17], v[16:17], v[32:33] op_sel_hi:[1,0]
	v_pk_mul_f32 v[18:19], v[18:19], v[32:33] op_sel_hi:[1,0]
	v_lshl_add_u64 v[36:37], v[64:65], 0, s[2:3]
	s_mov_b64 s[2:3], 0
	s_waitcnt vmcnt(0)
	v_cvt_f32_f16_e32 v40, v38
	v_cvt_f32_f16_sdwa v41, v38 dst_sel:DWORD dst_unused:UNUSED_PAD src0_sel:WORD_1
	v_cvt_f32_f16_e32 v38, v39
	v_cvt_f32_f16_sdwa v39, v39 dst_sel:DWORD dst_unused:UNUSED_PAD src0_sel:WORD_1
	v_pk_mul_f32 v[16:17], v[16:17], v[40:41]
	s_nop 0
	v_cvt_pk_f16_f32 v16, v16, v17
	v_pk_mul_f32 v[18:19], v[18:19], v[38:39]
	s_nop 0
	v_cvt_pk_f16_f32 v17, v18, v19
	v_add_co_u32_e32 v18, vcc, 0x9000, v64
	s_nop 1
	v_addc_co_u32_e32 v19, vcc, 0, v65, vcc
	global_store_dwordx2 v[18:19], v[16:17], off

; template <int MB>
; DI void out_tile(const Params& P, int layer, int row0, int nt, char* smem) {
;     ...
; #pragma unroll
;   for (int mb = 0; mb < MB; ++mb) {
;     const int row = row0 + wr * 32 * MB + mb * 32 + r32;
;     const float* src; float* dst; int b;
;     if (row < T_LAT) { b = row >> 11; src = (layer == 0 ? P.x : P.out) + (size_t)row * D; dst = P.out + (size_t)row * D; }
;     else { const int rc = row - T_LAT; b = 16; src = (layer == 0 ? P.ctx : ctxw) + (size_t)rc * D; dst = ctxw + (size_t)rc * D; }
;     const float* gt = mods + b * 3072 + 2048;
; #pragma unroll
;     for (int nb = 0; nb < 2; ++nb)
; #pragma unroll
;       for (int g = 0; g < 4; ++g) {
;         const int col = nt * 256 + wc * 64 + nb * 32 + 8 * g + 4 * hh;
;         const float4 xo = *(const float4*)(src + col);
;         const float4 gv = *(const float4*)(gt + col);
;         float4 r;
;         r.x = xo.x + gv.x * acc[mb][nb][4 * g]; r.y = xo.y + gv.y * acc[mb][nb][4 * g + 1];
;         r.z = xo.z + gv.z * acc[mb][nb][4 * g + 2]; r.w = xo.w + gv.w * acc[mb][nb][4 * g + 3];
;         *(float4*)(dst + col) = r;
;       }
;   }
.LBB0_746:
	s_or_b64 exec, exec, s[2:3]
	v_lshrrev_b32_e32 v37, 3, v40
	v_and_b32_e32 v36, 0xc0, v40
	s_lshl_b32 s2, s80, 8
	v_and_b32_e32 v37, 4, v37
	v_or3_b32 v40, v36, s2, v37
	v_lshl_add_u64 v[34:35], v[34:35], 2, s[60:61]
	s_mov_b64 s[2:3], 0x1002000
	v_lshl_add_u64 v[36:37], v[34:35], 0, s[2:3]
	v_lshlrev_b32_e32 v128, 2, v40
	v_lshl_add_u64 v[34:35], v[32:33], 0, v[128:129]
	v_lshl_add_u64 v[42:43], v[36:37], 0, v[128:129]
	v_lshl_add_u64 v[32:33], v[38:39], 0, v[128:129]
	v_readlane_b32 s36, v255, 26
	v_readlane_b32 s48, v255, 30
	v_readlane_b32 s37, v255, 27
	v_readlane_b32 s49, v255, 31
	s_mov_b64 s[64:65], 0x14e8180
	s_mov_b64 s[66:67], 0x7f66180
	s_mov_b64 s[96:97], 0x152c180
	s_mov_b64 vcc, 0x150a180
	global_load_dwordx4 v[162:165], v[42:43], off
	global_load_dwordx4 v[166:169], v[42:43], off offset:32
	global_load_dwordx4 v[170:173], v[42:43], off offset:64
	global_load_dwordx4 v[174:177], v[42:43], off offset:96
	global_load_dwordx4 v[178:181], v[42:43], off offset:128
	global_load_dwordx4 v[182:185], v[42:43], off offset:160
	global_load_dwordx4 v[186:189], v[42:43], off offset:192
	global_load_dwordx4 v[190:193], v[42:43], off offset:224
	global_load_dwordx4 v[130:133], v[34:35], off
	global_load_dwordx4 v[134:137], v[34:35], off offset:32
	global_load_dwordx4 v[138:141], v[34:35], off offset:64
	global_load_dwordx4 v[142:145], v[34:35], off offset:96
	global_load_dwordx4 v[146:149], v[34:35], off offset:128
	global_load_dwordx4 v[150:153], v[34:35], off offset:160
	global_load_dwordx4 v[154:157], v[34:35], off offset:192
	global_load_dwordx4 v[158:161], v[34:35], off offset:224
	s_waitcnt vmcnt(7)
	v_pk_fma_f32 v[16:17], v[16:17], v[162:163], v[130:131]
	v_pk_fma_f32 v[18:19], v[18:19], v[164:165], v[132:133]
	global_store_dwordx4 v[32:33], v[16:19], off
	s_waitcnt vmcnt(7)
	v_pk_fma_f32 v[20:21], v[20:21], v[166:167], v[134:135]
	v_pk_fma_f32 v[22:23], v[22:23], v[168:169], v[136:137]
	global_store_dwordx4 v[32:33], v[20:23], off offset:32
	s_waitcnt vmcnt(7)
	v_pk_fma_f32 v[24:25], v[24:25], v[170:171], v[138:139]
	v_pk_fma_f32 v[26:27], v[26:27], v[172:173], v[140:141]
	global_store_dwordx4 v[32:33], v[24:27], off offset:64
	s_waitcnt vmcnt(7)
	v_pk_fma_f32 v[28:29], v[28:29], v[174:175], v[142:143]
	v_pk_fma_f32 v[30:31], v[30:31], v[176:177], v[144:145]
	global_store_dwordx4 v[32:33], v[28:31], off offset:96
	s_waitcnt vmcnt(7)
	v_pk_fma_f32 v[0:1], v[0:1], v[178:179], v[146:147]
	v_pk_fma_f32 v[2:3], v[2:3], v[180:181], v[148:149]
	global_store_dwordx4 v[32:33], v[0:3], off offset:128
	s_waitcnt vmcnt(7)
	v_pk_fma_f32 v[4:5], v[4:5], v[182:183], v[150:151]
	v_pk_fma_f32 v[6:7], v[6:7], v[184:185], v[152:153]
	global_store_dwordx4 v[32:33], v[4:7], off offset:160
	s_waitcnt vmcnt(7)
	v_pk_fma_f32 v[8:9], v[8:9], v[186:187], v[154:155]
	v_pk_fma_f32 v[10:11], v[10:11], v[188:189], v[156:157]
	global_store_dwordx4 v[32:33], v[8:11], off offset:192
	s_waitcnt vmcnt(7)
	v_pk_fma_f32 v[12:13], v[12:13], v[190:191], v[158:159]
	v_pk_fma_f32 v[14:15], v[14:15], v[192:193], v[160:161]
	global_store_dwordx4 v[32:33], v[12:15], off offset:224
	v_or_b32_e32 v128, 0xe0, v128
